# grid barrier between the cross-attention query GEMM and the cross-attention tasks replaced by a workgroup barrier: tasks re-dealt so each workgroup consumes the queries of its own two GEMM units (12 g
# speedup vs baseline: 1.0201x; 1.0047x over previous
.LBB0_2433:
	s_cmp_gt_i32 s87, 12
	s_cselect_b64 s[2:3], -1, 0
	s_and_b64 s[0:1], s[4:5], s[2:3]
	s_andn2_b64 vcc, exec, s[0:1]
	s_cbranch_vccnz .LBB0_2487
	s_waitcnt vmcnt(0)
	s_waitcnt vmcnt(0)
	s_barrier
	s_mov_b64 s[0:1], exec
	v_readlane_b32 s4, v251, 1
	v_readlane_b32 s5, v251, 2
	s_and_b64 s[4:5], s[0:1], s[4:5]
.LBB0_2486:
	s_or_b64 exec, exec, s[0:1]
	s_waitcnt lgkmcnt(0)
	s_barrier

.LBB0_2491:
	s_and_b32 s76, s18, 7
	s_lshl_b32 s76, s76, 7
	s_bfe_u32 s77, s18, 0x10009
	s_lshl_b32 s77, s77, 6
	s_or_b32 s76, s76, s77
	s_bfe_u32 s77, s18, 0x20006
	s_lshl_b32 s77, s77, 4
	s_or_b32 s76, s76, s77
	s_bfe_u32 s77, s18, 0x30003
	s_lshl_b32 s77, s77, 1
	s_or_b32 s76, s76, s77
	s_bfe_u32 s77, s18, 0x10008
	s_or_b32 s76, s76, s77
	s_lshl_b32 s6, s76, 7
	s_ashr_i32 s14, s76, 6
	s_and_b32 s6, s6, 0x780
	s_ashr_i32 s15, s14, 31
	v_add_u32_e32 v138, s6, v137
	s_bfe_u32 s24, s76, 0x20004
	s_lshl_b64 s[20:21], s[14:15], 21
	v_lshlrev_b64 v[0:1], 10, v[138:139]
	v_lshl_add_u64 v[184:185], s[20:21], 0, v[0:1]
	s_lshl_b32 s19, s24, 8
	s_lshl_b32 s6, s24, 9
	s_lshl_b64 s[20:21], s[14:15], 19
	s_add_u32 s15, s9, s20
	v_lshl_add_u64 v[0:1], v[184:185], 1, s[2:3]
	s_addc_u32 s23, s16, s21
	v_lshl_add_u64 v[0:1], v[0:1], 0, s[6:7]
	v_mov_b32_e32 v163, v139
	s_add_u32 s22, s15, s6
	v_lshl_add_u64 v[0:1], v[0:1], 0, v[162:163]
	s_addc_u32 s23, s23, 0
	s_lshl_b32 s14, s14, 2
	s_or_b32 s14, s14, s24
	global_load_dwordx4 v[20:23], v[0:1], off
	global_load_dwordx4 v[24:27], v[0:1], off offset:64
	global_load_dwordx4 v[28:31], v[0:1], off offset:128
	global_load_dwordx4 v[32:35], v[0:1], off offset:192
	global_load_dwordx4 v[36:39], v[0:1], off offset:256
	global_load_dwordx4 v[44:47], v[0:1], off offset:320
	global_load_dwordx4 v[48:51], v[0:1], off offset:384
	global_load_dwordx4 v[52:55], v[0:1], off offset:448
	s_ashr_i32 s15, s14, 31
	v_mov_b32_e32 v165, v139
	s_lshl_b64 s[14:15], s[14:15], 17
	v_lshl_add_u64 v[0:1], s[22:23], 0, v[164:165]
	v_mov_b32_e32 v167, v139
	v_lshl_add_u64 v[2:3], v[142:143], 0, s[14:15]
	v_lshl_add_u64 v[4:5], v[0:1], 0, v[166:167]
	v_mov_b32_e32 v169, v139
	v_mov_b32_e32 v171, v139
	v_lshl_add_u64 v[6:7], v[2:3], 0, v[168:169]
	global_load_dwordx4 v[60:63], v[4:5], off
	global_load_dwordx4 v[64:67], v[6:7], off
	v_lshl_add_u64 v[4:5], v[0:1], 0, v[170:171]
	v_mov_b32_e32 v173, v139
	v_mov_b32_e32 v175, v139
	v_mov_b32_e32 v179, v139
	v_lshl_add_u64 v[6:7], v[2:3], 0, v[172:173]
	global_load_dwordx4 v[72:75], v[4:5], off
	global_load_dwordx4 v[80:83], v[6:7], off
	v_lshl_add_u64 v[4:5], v[0:1], 0, v[174:175]
	v_mov_b32_e32 v177, v139
	v_lshl_add_u64 v[0:1], v[0:1], 0, v[178:179]
	v_mov_b32_e32 v181, v139
	v_lshl_add_u64 v[6:7], v[2:3], 0, v[176:177]
	global_load_dwordx4 v[84:87], v[4:5], off
	global_load_dwordx4 v[88:91], v[6:7], off
	v_lshl_add_u64 v[2:3], v[2:3], 0, v[180:181]
	global_load_dwordx4 v[100:103], v[0:1], off
	global_load_dwordx4 v[104:107], v[2:3], off
	s_or_b32 s20, s20, s6
	v_lshl_add_u64 v[186:187], v[144:145], 0, s[14:15]
	v_lshl_add_u64 v[188:189], v[146:147], 0, s[14:15]
	v_lshl_add_u64 v[190:191], v[148:149], 0, s[14:15]
	v_lshl_add_u64 v[192:193], v[150:151], 0, s[14:15]
	v_lshl_add_u64 v[194:195], s[20:21], 0, v[154:155]
	v_lshl_add_u64 v[196:197], s[20:21], 0, v[156:157]
	v_lshl_add_u64 v[198:199], s[20:21], 0, v[158:159]
	v_lshl_add_u64 v[200:201], s[20:21], 0, v[160:161]
	v_mov_b32_e32 v128, 0xf149f2ca
	s_mov_b64 s[14:15], 0
	s_mov_b32 s6, 4
	v_mov_b32_e32 v163, 0
	v_mov_b32_e32 v0, 0
	v_mov_b32_e32 v1, v139
	v_mov_b32_e32 v2, v139
	v_mov_b32_e32 v3, v139
	v_mov_b32_e32 v4, 0
	v_mov_b32_e32 v5, v139
	v_mov_b32_e32 v6, v139
	v_mov_b32_e32 v7, v139
	v_mov_b32_e32 v8, 0
	v_mov_b32_e32 v9, v139
	v_mov_b32_e32 v10, v139
	v_mov_b32_e32 v11, v139
	v_mov_b32_e32 v12, 0
	v_mov_b32_e32 v13, v139
	v_mov_b32_e32 v14, v139
	v_mov_b32_e32 v15, v139
	v_mov_b32_e32 v16, 0
	v_mov_b32_e32 v17, v139
	v_mov_b32_e32 v18, v139
	v_mov_b32_e32 v19, v139
	v_mov_b32_e32 v40, 0
	v_mov_b32_e32 v41, v139
	s_waitcnt vmcnt(0)
	v_mov_b32_e32 v42, v139
	v_mov_b32_e32 v43, v139
	v_mov_b32_e32 v56, 0
	v_mov_b32_e32 v57, v139
	v_mov_b32_e32 v58, v139
	v_mov_b32_e32 v59, v139
	v_mov_b32_e32 v68, 0
	v_mov_b32_e32 v69, v139
	v_mov_b32_e32 v70, v139
	v_mov_b32_e32 v71, v139
	v_mov_b32_e32 v76, 0
	v_mov_b32_e32 v77, v139
	v_mov_b32_e32 v78, v139
	v_mov_b32_e32 v79, v139
	v_mov_b32_e32 v92, 0
	v_mov_b32_e32 v93, v139
	v_mov_b32_e32 v94, v139
	v_mov_b32_e32 v95, v139
	v_mov_b32_e32 v96, 0
	v_mov_b32_e32 v97, v139
	v_mov_b32_e32 v98, v139
	v_mov_b32_e32 v99, v139
	v_mov_b32_e32 v108, 0
	v_mov_b32_e32 v109, v139
	v_mov_b32_e32 v110, v139
	v_mov_b32_e32 v111, v139
	v_mov_b32_e32 v112, 0
	v_mov_b32_e32 v113, v139
	v_mov_b32_e32 v114, v139
	v_mov_b32_e32 v115, v139
	v_mov_b32_e32 v116, 0
	v_mov_b32_e32 v117, v139
	v_mov_b32_e32 v118, v139
	v_mov_b32_e32 v119, v139
	v_mov_b32_e32 v120, 0
	v_mov_b32_e32 v121, v139
	v_mov_b32_e32 v122, v139
	v_mov_b32_e32 v123, v139
	v_mov_b32_e32 v124, 0
	v_mov_b32_e32 v125, v139
	v_mov_b32_e32 v126, v139
	v_mov_b32_e32 v127, v139
